# FoX item epilogue: gate and out_gain loads hoisted to one round trip
# baseline (speedup 1.0000x reference)
; __device__ __forceinline__ float bflo(unsigned u) { return __uint_as_float(u << 16); }
; __device__ __forceinline__ float bfhi(unsigned u) { return __uint_as_float(u & 0xffff0000u); }
; __device__ __forceinline__ float silu(float g) { return g * __builtin_amdgcn_rcpf(1.0f + __expf(-g)); }
; template <int MODE>
; __device__ __forceinline__ void attn_item(const AttnP& p, int b, int h, int qb, LAS unsigned char* lds) {
;     ...
;     float inv0 = 1.f, inv1 = 0.f;
;     if (MODE != 1) { float l0 = lsum[0]; l0 += __shfl_xor(l0, 32); inv0 = 1.0f / l0; }
;     if (MODE == 0) { float l1 = lsum[NC - 1]; l1 += __shfl_xor(l1, 32); inv1 = p.lam / l1; }
;     float ss = 0.f;
; #pragma unroll
;     for (int d = 0; d < DV / 32; ++d)
; #pragma unroll
;         for (int i = 0; i < 16; ++i) {
;             float o = O[0][d][i] * inv0;
;             if (MODE == 0) o -= O[NC - 1][d][i] * inv1;
;             O[0][d][i] = o; ss += o * o;
;         }
;     ss += __shfl_xor(ss, 32);
;     float rn = 1.0f / sqrtf(ss * (1.0f / DV) + 1e-6f);
;     if (MODE == 0) rn *= p.oml;
;     int qrow_e = qrow; asm volatile("" : "+v"(qrow_e));
;     const size_t trow = (size_t)(tok0 + qrow_e);
; #pragma unroll
;     for (int d = 0; d < DV / 32; ++d)
; #pragma unroll
;         for (int g = 0; g < 4; ++g) {
;             const int dd = d * 32 + 8 * g + 4 * hh;
;             const u32x2 gr = *(const u32x2*)(P + trow * PP + gcol + dd);
;             const f32x4 og = *(const f32x4*)(p.out_gain + gaincol + dd);
;             const float o0 = O[0][d][4 * g] * rn * og[0] * silu(bflo(gr.x)), o1 = O[0][d][4 * g + 1] * rn * og[1] * silu(bfhi(gr.x));
;             const float o2 = O[0][d][4 * g + 2] * rn * og[2] * silu(bflo(gr.y)), o3 = O[0][d][4 * g + 3] * rn * og[3] * silu(bfhi(gr.y));
.LBB0_242:
	ds_bpermute_b32 v2, v114, v0
	s_lshl_b32 s2, s20, 2
	s_bitset1_b32 s2, 12
	s_waitcnt lgkmcnt(0)
	v_add_f32_e32 v0, v0, v2
	v_div_scale_f32 v2, s[0:1], v0, v0, 1.0
	v_rcp_f32_e32 v3, v2
	s_nop 0
	v_fma_f32 v4, -v2, v3, 1.0
	v_fmac_f32_e32 v3, v4, v3
	v_div_scale_f32 v4, vcc, 1.0, v0, 1.0
	v_mul_f32_e32 v5, v4, v3
	v_fma_f32 v6, -v2, v5, v4
	v_fmac_f32_e32 v5, v6, v3
	v_fma_f32 v2, -v2, v5, v4
	v_div_fmas_f32 v2, v2, v3, v5
	v_div_fixup_f32 v56, v2, v0, 1.0
	v_add_u32_e32 v2, s26, v115
	v_mov_b64_e32 v[4:5], s[68:69]
	v_mad_i64_i32 v[4:5], s[0:1], v2, s76, v[4:5]
	v_lshl_add_u64 v[4:5], v[4:5], 0, s[92:93]
	v_lshlrev_b32_e32 v0, 1, v94
	v_lshl_add_u64 v[12:13], v[4:5], 0, v[0:1]
	s_waitcnt vmcnt(0)
	global_load_dwordx2 v[50:51], v[12:13], off offset:3072
	global_load_dwordx2 v[54:55], v[12:13], off offset:3088
	global_load_dwordx2 v[66:67], v[12:13], off offset:3104
	global_load_dwordx2 v[74:75], v[12:13], off offset:3120
	v_readlane_b32 s0, v254, 54
	v_readlane_b32 s1, v254, 55
	s_add_u32 s2, s0, s2
	v_ashrrev_i32_e32 v3, 31, v2
	s_addc_u32 s3, s1, 0
	v_readlane_b32 s0, v254, 40
	v_lshlrev_b64 v[10:11], 11, v[2:3]
	v_readlane_b32 s1, v254, 41
	global_load_dwordx2 v[76:77], v[12:13], off offset:3136
	global_load_dwordx2 v[86:87], v[12:13], off offset:3152
	v_lshl_add_u64 v[10:11], s[0:1], 0, v[10:11]
	v_lshl_add_u64 v[10:11], v[10:11], 0, s[92:93]
	v_lshl_add_u64 v[10:11], v[10:11], 0, v[0:1]
	v_pk_mul_f32 v[14:15], v[26:27], v[56:57] op_sel_hi:[1,0]
	v_pk_mul_f32 v[8:9], v[28:29], v[56:57] op_sel_hi:[1,0]
	v_pk_mul_f32 v[6:7], v[30:31], v[56:57] op_sel_hi:[1,0]
	v_lshlrev_b32_e32 v57, 2, v94
	global_load_dwordx4 v[2:5], v57, s[2:3]
	global_load_dwordx4 v[140:143], v57, s[2:3] offset:32
	global_load_dwordx4 v[144:147], v57, s[2:3] offset:64
	global_load_dwordx4 v[148:151], v57, s[2:3] offset:96
	global_load_dwordx4 v[152:155], v57, s[2:3] offset:128
	global_load_dwordx4 v[156:159], v57, s[2:3] offset:160
	global_load_dwordx4 v[160:163], v57, s[2:3] offset:192
	global_load_dwordx4 v[164:167], v57, s[2:3] offset:224
	global_load_dwordx2 v[168:169], v[12:13], off offset:3168
	global_load_dwordx2 v[170:171], v[12:13], off offset:3184
	v_pk_mul_f32 v[32:33], v[32:33], v[56:57] op_sel_hi:[1,0]
	v_pk_mul_f32 v[34:35], v[34:35], v[56:57] op_sel_hi:[1,0]
	v_pk_mul_f32 v[64:65], v[32:33], v[32:33]
	v_pk_mul_f32 v[62:63], v[34:35], v[34:35]
	v_pk_mul_f32 v[36:37], v[36:37], v[56:57] op_sel_hi:[1,0]
	v_pk_mul_f32 v[38:39], v[38:39], v[56:57] op_sel_hi:[1,0]
	v_pk_mul_f32 v[72:73], v[36:37], v[36:37]
	v_pk_mul_f32 v[70:71], v[38:39], v[38:39]
	v_pk_mul_f32 v[42:43], v[42:43], v[56:57] op_sel_hi:[1,0]
	v_pk_mul_f32 v[46:47], v[46:47], v[56:57] op_sel_hi:[1,0]
	v_pk_mul_f32 v[78:79], v[42:43], v[42:43]
	v_pk_mul_f32 v[88:89], v[46:47], v[46:47]
	v_pk_mul_f32 v[16:17], v[16:17], v[56:57] op_sel_hi:[1,0]
	v_pk_mul_f32 v[18:19], v[18:19], v[56:57] op_sel_hi:[1,0]
	v_pk_mul_f32 v[94:95], v[16:17], v[16:17]
	v_pk_mul_f32 v[92:93], v[18:19], v[18:19]
	v_pk_mul_f32 v[22:23], v[22:23], v[56:57] op_sel_hi:[1,0]
	v_pk_mul_f32 v[24:25], v[24:25], v[56:57] op_sel_hi:[1,0]
	v_pk_mul_f32 v[96:97], v[22:23], v[22:23]
	v_pk_mul_f32 v[100:101], v[24:25], v[24:25]
	v_pk_mul_f32 v[26:27], v[14:15], v[14:15]
	v_pk_mul_f32 v[28:29], v[8:9], v[8:9]
	v_pk_mul_f32 v[30:31], v[6:7], v[6:7]
	s_waitcnt vmcnt(0) lgkmcnt(0)
	v_lshlrev_b32_e32 v48, 16, v50
	v_and_b32_e32 v49, 0xffff0000, v50
	v_mul_f32_e32 v50, 0xbfb8aa3b, v48
	v_exp_f32_e32 v50, v50
	s_nop 0
	v_add_f32_e32 v50, 1.0, v50
	v_rcp_f32_e32 v52, v50
	v_mul_f32_e32 v50, 0xbfb8aa3b, v49
	v_exp_f32_e32 v50, v50
	s_nop 0
	v_add_f32_e32 v50, 1.0, v50
	v_rcp_f32_e32 v53, v50
	v_lshlrev_b32_e32 v50, 16, v51
	v_and_b32_e32 v51, 0xffff0000, v51
	v_pk_mul_f32 v[48:49], v[52:53], v[48:49]
	v_mul_f32_e32 v52, 0xbfb8aa3b, v50
	v_mul_f32_e32 v53, 0xbfb8aa3b, v51
	v_exp_f32_e32 v52, v52
	v_exp_f32_e32 v53, v53
	v_add_f32_e32 v52, 1.0, v52
	v_add_f32_e32 v53, 1.0, v53
	v_rcp_f32_e32 v52, v52
	v_rcp_f32_e32 v53, v53
	s_nop 0
	v_pk_mul_f32 v[50:51], v[52:53], v[50:51]
	v_lshlrev_b32_e32 v52, 16, v54
	v_mul_f32_e32 v0, 0xbfb8aa3b, v52
	v_exp_f32_e32 v0, v0
	v_and_b32_e32 v53, 0xffff0000, v54
	v_lshlrev_b32_e32 v54, 16, v55
	v_and_b32_e32 v55, 0xffff0000, v55
	v_add_f32_e32 v0, 1.0, v0
	v_rcp_f32_e32 v58, v0
	v_mul_f32_e32 v0, 0xbfb8aa3b, v53
	v_exp_f32_e32 v0, v0
	s_nop 0
	v_add_f32_e32 v0, 1.0, v0
	v_rcp_f32_e32 v59, v0
	v_mul_f32_e32 v0, 0xbfb8aa3b, v54
	v_exp_f32_e32 v0, v0
	v_pk_mul_f32 v[52:53], v[58:59], v[52:53]
	v_add_f32_e32 v0, 1.0, v0
	v_rcp_f32_e32 v58, v0
	v_mul_f32_e32 v0, 0xbfb8aa3b, v55
	v_exp_f32_e32 v0, v0
	s_nop 0
	v_add_f32_e32 v0, 1.0, v0
	v_rcp_f32_e32 v59, v0
	s_nop 0
	v_pk_mul_f32 v[54:55], v[58:59], v[54:55]
	v_pk_mul_f32 v[58:59], v[40:41], v[56:57] op_sel_hi:[1,0]
	v_lshlrev_b32_e32 v40, 16, v66
	v_mul_f32_e32 v0, 0xbfb8aa3b, v40
	v_exp_f32_e32 v0, v0
	v_and_b32_e32 v41, 0xffff0000, v66
	v_pk_mul_f32 v[80:81], v[58:59], v[58:59]
	v_add_f32_e32 v0, 1.0, v0
	v_rcp_f32_e32 v60, v0
	v_mul_f32_e32 v0, 0xbfb8aa3b, v41
	v_exp_f32_e32 v0, v0
	s_nop 0
	v_add_f32_e32 v0, 1.0, v0
	v_rcp_f32_e32 v61, v0
	s_nop 0
	v_pk_mul_f32 v[60:61], v[60:61], v[40:41]
	v_lshlrev_b32_e32 v40, 16, v67
	v_mul_f32_e32 v0, 0xbfb8aa3b, v40
	v_exp_f32_e32 v0, v0
	v_and_b32_e32 v41, 0xffff0000, v67
	v_add_f32_e32 v0, 1.0, v0
	v_rcp_f32_e32 v66, v0
	v_mul_f32_e32 v0, 0xbfb8aa3b, v41
	v_exp_f32_e32 v0, v0
	s_nop 0
	v_add_f32_e32 v0, 1.0, v0
	v_rcp_f32_e32 v67, v0
	s_nop 0
	v_pk_mul_f32 v[40:41], v[66:67], v[40:41]
	v_pk_mul_f32 v[66:67], v[44:45], v[56:57] op_sel_hi:[1,0]
	v_lshlrev_b32_e32 v44, 16, v74
	v_mul_f32_e32 v0, 0xbfb8aa3b, v44
; __device__ __forceinline__ float bflo(unsigned u) { return __uint_as_float(u << 16); }
; __device__ __forceinline__ float bfhi(unsigned u) { return __uint_as_float(u & 0xffff0000u); }
; __device__ __forceinline__ float silu(float g) { return g * __builtin_amdgcn_rcpf(1.0f + __expf(-g)); }
; template <int MODE>
; __device__ __forceinline__ void attn_item(const AttnP& p, int b, int h, int qb, LAS unsigned char* lds) {
;     ...
;             O[0][d][i] = o; ss += o * o;
;         }
;     ss += __shfl_xor(ss, 32);
;     float rn = 1.0f / sqrtf(ss * (1.0f / DV) + 1e-6f);
;     if (MODE == 0) rn *= p.oml;
;     int qrow_e = qrow; asm volatile("" : "+v"(qrow_e));
;     const size_t trow = (size_t)(tok0 + qrow_e);
; #pragma unroll
;     for (int d = 0; d < DV / 32; ++d)
; #pragma unroll
;         for (int g = 0; g < 4; ++g) {
;             const int dd = d * 32 + 8 * g + 4 * hh;
;             const u32x2 gr = *(const u32x2*)(P + trow * PP + gcol + dd);
;             const f32x4 og = *(const f32x4*)(p.out_gain + gaincol + dd);
;             const float o0 = O[0][d][4 * g] * rn * og[0] * silu(bflo(gr.x)), o1 = O[0][d][4 * g + 1] * rn * og[1] * silu(bfhi(gr.x));
;             const float o2 = O[0][d][4 * g + 2] * rn * og[2] * silu(bflo(gr.y)), o3 = O[0][d][4 * g + 3] * rn * og[3] * silu(bfhi(gr.y));
	v_exp_f32_e32 v0, v0
	v_and_b32_e32 v45, 0xffff0000, v74
	v_pk_mul_f32 v[90:91], v[66:67], v[66:67]
	v_add_f32_e32 v0, 1.0, v0
	v_rcp_f32_e32 v68, v0
	v_mul_f32_e32 v0, 0xbfb8aa3b, v45
	v_exp_f32_e32 v0, v0
	s_nop 0
	v_add_f32_e32 v0, 1.0, v0
	v_rcp_f32_e32 v69, v0
	s_nop 0
	v_pk_mul_f32 v[68:69], v[68:69], v[44:45]
	v_lshlrev_b32_e32 v44, 16, v75
	v_mul_f32_e32 v0, 0xbfb8aa3b, v44
	v_exp_f32_e32 v0, v0
	v_and_b32_e32 v45, 0xffff0000, v75
	v_add_f32_e32 v0, 1.0, v0
	v_rcp_f32_e32 v74, v0
	v_mul_f32_e32 v0, 0xbfb8aa3b, v45
	v_exp_f32_e32 v0, v0
	s_nop 0
	v_add_f32_e32 v0, 1.0, v0
	v_rcp_f32_e32 v75, v0
	s_nop 0
	v_pk_mul_f32 v[44:45], v[74:75], v[44:45]
	v_lshlrev_b32_e32 v74, 16, v76
	v_mul_f32_e32 v0, 0xbfb8aa3b, v74
	v_exp_f32_e32 v0, v0
	v_and_b32_e32 v75, 0xffff0000, v76
	v_lshlrev_b32_e32 v76, 16, v77
	v_and_b32_e32 v77, 0xffff0000, v77
	v_add_f32_e32 v0, 1.0, v0
	v_rcp_f32_e32 v82, v0
	v_mul_f32_e32 v0, 0xbfb8aa3b, v75
	v_exp_f32_e32 v0, v0
	s_nop 0
	v_add_f32_e32 v0, 1.0, v0
	v_rcp_f32_e32 v83, v0
	v_mul_f32_e32 v0, 0xbfb8aa3b, v76
	v_exp_f32_e32 v0, v0
	v_pk_mul_f32 v[74:75], v[82:83], v[74:75]
	v_add_f32_e32 v0, 1.0, v0
	v_rcp_f32_e32 v82, v0
	v_mul_f32_e32 v0, 0xbfb8aa3b, v77
	v_exp_f32_e32 v0, v0
	s_nop 0
	v_add_f32_e32 v0, 1.0, v0
	v_rcp_f32_e32 v83, v0
	s_nop 0
	v_pk_mul_f32 v[76:77], v[82:83], v[76:77]
	v_pk_mul_f32 v[82:83], v[20:21], v[56:57] op_sel_hi:[1,0]
	v_lshlrev_b32_e32 v20, 16, v86
	v_mul_f32_e32 v0, 0xbfb8aa3b, v20
	v_exp_f32_e32 v0, v0
	v_and_b32_e32 v21, 0xffff0000, v86
	v_pk_mul_f32 v[98:99], v[82:83], v[82:83]
	v_add_f32_e32 v0, 1.0, v0
	v_rcp_f32_e32 v84, v0
	v_mul_f32_e32 v0, 0xbfb8aa3b, v21
	v_exp_f32_e32 v0, v0
	s_nop 0
	v_add_f32_e32 v0, 1.0, v0
	v_rcp_f32_e32 v85, v0
	s_nop 0
	v_pk_mul_f32 v[84:85], v[84:85], v[20:21]
	v_lshlrev_b32_e32 v20, 16, v87
	v_mul_f32_e32 v0, 0xbfb8aa3b, v20
	v_exp_f32_e32 v0, v0
	v_and_b32_e32 v21, 0xffff0000, v87
	v_add_f32_e32 v0, 1.0, v0
	v_rcp_f32_e32 v86, v0
	v_mul_f32_e32 v0, 0xbfb8aa3b, v21
	v_exp_f32_e32 v0, v0
	s_nop 0
	v_add_f32_e32 v0, 1.0, v0
	v_rcp_f32_e32 v87, v0
	v_add_f32_e32 v0, v64, v65
	v_add_f32_e32 v0, v62, v0
	v_add_f32_e32 v0, v63, v0
	v_add_f32_e32 v0, v72, v0
	v_add_f32_e32 v0, v73, v0
	v_add_f32_e32 v0, v70, v0
	v_add_f32_e32 v0, v71, v0
	v_add_f32_e32 v0, v80, v0
	v_add_f32_e32 v0, v81, v0
	v_add_f32_e32 v0, v78, v0
	v_add_f32_e32 v0, v79, v0
	v_add_f32_e32 v0, v90, v0
	v_add_f32_e32 v0, v91, v0
	v_add_f32_e32 v0, v88, v0
	v_add_f32_e32 v0, v89, v0
	v_add_f32_e32 v0, v94, v0
	v_add_f32_e32 v0, v95, v0
	v_add_f32_e32 v0, v92, v0
	v_add_f32_e32 v0, v93, v0
	v_add_f32_e32 v0, v98, v0
	v_add_f32_e32 v0, v99, v0
	v_add_f32_e32 v0, v96, v0
	v_add_f32_e32 v0, v97, v0
	v_add_f32_e32 v0, v100, v0
	v_add_f32_e32 v0, v101, v0
	v_add_f32_e32 v0, v26, v0
	v_add_f32_e32 v0, v27, v0
	v_add_f32_e32 v0, v28, v0
	v_add_f32_e32 v0, v29, v0
	v_add_f32_e32 v0, v30, v0
	v_add_f32_e32 v0, v31, v0
	ds_bpermute_b32 v26, v114, v0
	v_pk_mul_f32 v[86:87], v[86:87], v[20:21]
	v_mov_b64_e32 v[20:21], v[168:169]
	s_waitcnt lgkmcnt(0)
; __device__ __forceinline__ unsigned pk2(float lo, float hi) { f32x2 v = {lo, hi}; bf16x2_t b = __builtin_convertvector(v, bf16x2_t); return __builtin_bit_cast(unsigned, b); }
; __device__ __forceinline__ float bflo(unsigned u) { return __uint_as_float(u << 16); }
; __device__ __forceinline__ float bfhi(unsigned u) { return __uint_as_float(u & 0xffff0000u); }
; __device__ __forceinline__ float silu(float g) { return g * __builtin_amdgcn_rcpf(1.0f + __expf(-g)); }
; template <int MODE>
; __device__ __forceinline__ void attn_item(const AttnP& p, int b, int h, int qb, LAS unsigned char* lds) {
;     ...
;     ss += __shfl_xor(ss, 32);
;     float rn = 1.0f / sqrtf(ss * (1.0f / DV) + 1e-6f);
;     if (MODE == 0) rn *= p.oml;
;     int qrow_e = qrow; asm volatile("" : "+v"(qrow_e));
;     const size_t trow = (size_t)(tok0 + qrow_e);
; #pragma unroll
;     for (int d = 0; d < DV / 32; ++d)
; #pragma unroll
;         for (int g = 0; g < 4; ++g) {
;             const int dd = d * 32 + 8 * g + 4 * hh;
;             const u32x2 gr = *(const u32x2*)(P + trow * PP + gcol + dd);
;             const f32x4 og = *(const f32x4*)(p.out_gain + gaincol + dd);
;             const float o0 = O[0][d][4 * g] * rn * og[0] * silu(bflo(gr.x)), o1 = O[0][d][4 * g + 1] * rn * og[1] * silu(bfhi(gr.x));
;             const float o2 = O[0][d][4 * g + 2] * rn * og[2] * silu(bflo(gr.y)), o3 = O[0][d][4 * g + 3] * rn * og[3] * silu(bfhi(gr.y));
;             u32x2 wv; wv.x = pk2(o0, o1); wv.y = pk2(o2, o3);
;             *(u32x2*)(p.mixed + trow * 1024 + mixcol + dd) = wv;
;         }
	v_add_f32_e32 v0, v0, v26
	v_fmamk_f32 v0, v0, 0x3c800000, v211
	v_cmp_gt_f32_e32 vcc, s55, v0
	v_mul_f32_e32 v26, 0x4f800000, v0
	s_nop 0
	v_cndmask_b32_e32 v0, v0, v26, vcc
	v_sqrt_f32_e32 v26, v0
	s_nop 0
	v_add_u32_e32 v27, -1, v26
	v_fma_f32 v28, -v27, v26, v0
	v_cmp_ge_f32_e64 s[0:1], 0, v28
	v_add_u32_e32 v28, 1, v26
	s_nop 0
	v_cndmask_b32_e64 v27, v26, v27, s[0:1]
	v_fma_f32 v26, -v28, v26, v0
	v_cmp_lt_f32_e64 s[0:1], 0, v26
	s_nop 1
	v_cndmask_b32_e64 v26, v27, v28, s[0:1]
	v_mul_f32_e32 v27, 0x37800000, v26
	v_cndmask_b32_e32 v26, v26, v27, vcc
	v_cmp_class_f32_e32 vcc, v0, v212
	s_nop 1
	v_cndmask_b32_e32 v0, v26, v0, vcc
	v_div_scale_f32 v26, s[0:1], v0, v0, 1.0
	v_rcp_f32_e32 v27, v26
	s_mov_b64 s[0:1], 0
	v_fma_f32 v28, -v26, v27, 1.0
	v_fmac_f32_e32 v27, v28, v27
	v_div_scale_f32 v28, vcc, 1.0, v0, 1.0
	v_mul_f32_e32 v29, v28, v27
	v_fma_f32 v30, -v26, v29, v28
	v_fmac_f32_e32 v29, v30, v27
	v_fma_f32 v26, -v26, v29, v28
	v_div_fmas_f32 v26, v26, v27, v29
	v_div_fixup_f32 v0, v26, v0, 1.0
	v_pk_mul_f32 v[26:27], v[32:33], v[0:1] op_sel_hi:[1,0]
	v_pk_mul_f32 v[16:17], v[16:17], v[0:1] op_sel_hi:[1,0]
	v_pk_mul_f32 v[2:3], v[2:3], v[26:27]
	v_pk_mul_f32 v[26:27], v[34:35], v[0:1] op_sel_hi:[1,0]
	v_pk_mul_f32 v[2:3], v[48:49], v[2:3]
	v_pk_mul_f32 v[4:5], v[4:5], v[26:27]
	v_cvt_pk_bf16_f32 v2, v2, v3
	v_pk_mul_f32 v[4:5], v[50:51], v[4:5]
	v_pk_mul_f32 v[26:27], v[36:37], v[0:1] op_sel_hi:[1,0]
	v_cvt_pk_bf16_f32 v3, v4, v5
	global_store_dwordx2 v[10:11], v[2:3], off
	s_nop 1
	v_mov_b64_e32 v[2:3], v[140:141]
	v_mov_b64_e32 v[4:5], v[142:143]
	v_pk_mul_f32 v[14:15], v[14:15], v[0:1] op_sel_hi:[1,0]
	v_pk_mul_f32 v[8:9], v[8:9], v[0:1] op_sel_hi:[1,0]
	v_pk_mul_f32 v[6:7], v[6:7], v[0:1] op_sel_hi:[1,0]
	v_pk_mul_f32 v[2:3], v[2:3], v[26:27]
	v_pk_mul_f32 v[26:27], v[38:39], v[0:1] op_sel_hi:[1,0]
	v_pk_mul_f32 v[2:3], v[52:53], v[2:3]
	v_pk_mul_f32 v[4:5], v[4:5], v[26:27]
	v_cvt_pk_bf16_f32 v2, v2, v3
	v_pk_mul_f32 v[4:5], v[54:55], v[4:5]
	v_pk_mul_f32 v[26:27], v[58:59], v[0:1] op_sel_hi:[1,0]
	v_cvt_pk_bf16_f32 v3, v4, v5
	global_store_dwordx2 v[10:11], v[2:3], off offset:16
	s_nop 1
	v_mov_b64_e32 v[2:3], v[144:145]
	v_mov_b64_e32 v[4:5], v[146:147]
	v_pk_mul_f32 v[2:3], v[2:3], v[26:27]
	v_pk_mul_f32 v[26:27], v[42:43], v[0:1] op_sel_hi:[1,0]
	v_pk_mul_f32 v[2:3], v[60:61], v[2:3]
	v_pk_mul_f32 v[4:5], v[4:5], v[26:27]
	v_cvt_pk_bf16_f32 v2, v2, v3
	v_pk_mul_f32 v[4:5], v[40:41], v[4:5]
	v_pk_mul_f32 v[26:27], v[66:67], v[0:1] op_sel_hi:[1,0]
	v_cvt_pk_bf16_f32 v3, v4, v5
	global_store_dwordx2 v[10:11], v[2:3], off offset:32
	s_nop 1
	v_mov_b64_e32 v[2:3], v[148:149]
	v_mov_b64_e32 v[4:5], v[150:151]
	v_pk_mul_f32 v[2:3], v[2:3], v[26:27]
	v_pk_mul_f32 v[26:27], v[46:47], v[0:1] op_sel_hi:[1,0]
	v_pk_mul_f32 v[2:3], v[68:69], v[2:3]
	v_pk_mul_f32 v[4:5], v[4:5], v[26:27]
	v_cvt_pk_bf16_f32 v2, v2, v3
	v_pk_mul_f32 v[4:5], v[44:45], v[4:5]
	s_nop 0
	v_cvt_pk_bf16_f32 v3, v4, v5
	global_store_dwordx2 v[10:11], v[2:3], off offset:48
	s_nop 1
	v_mov_b64_e32 v[2:3], v[152:153]
	v_mov_b64_e32 v[4:5], v[154:155]
	v_pk_mul_f32 v[2:3], v[2:3], v[16:17]
	v_pk_mul_f32 v[16:17], v[18:19], v[0:1] op_sel_hi:[1,0]
	v_pk_mul_f32 v[2:3], v[74:75], v[2:3]
	v_pk_mul_f32 v[4:5], v[4:5], v[16:17]
	v_cvt_pk_bf16_f32 v2, v2, v3
	v_pk_mul_f32 v[4:5], v[76:77], v[4:5]
	v_pk_mul_f32 v[16:17], v[82:83], v[0:1] op_sel_hi:[1,0]
	v_cvt_pk_bf16_f32 v3, v4, v5
	global_store_dwordx2 v[10:11], v[2:3], off offset:64
	s_nop 1
	v_mov_b64_e32 v[2:3], v[156:157]
	v_mov_b64_e32 v[4:5], v[158:159]
	v_pk_mul_f32 v[2:3], v[2:3], v[16:17]
	v_pk_mul_f32 v[16:17], v[22:23], v[0:1] op_sel_hi:[1,0]
	v_pk_mul_f32 v[2:3], v[84:85], v[2:3]
	v_pk_mul_f32 v[4:5], v[4:5], v[16:17]
	v_cvt_pk_bf16_f32 v2, v2, v3
	v_pk_mul_f32 v[4:5], v[86:87], v[4:5]
	v_lshlrev_b32_e32 v16, 16, v20
	v_cvt_pk_bf16_f32 v3, v4, v5
	global_store_dwordx2 v[10:11], v[2:3], off offset:80
	s_nop 1
	v_mov_b64_e32 v[2:3], v[160:161]
	v_mov_b64_e32 v[4:5], v[162:163]
	v_and_b32_e32 v17, 0xffff0000, v20
	v_mul_f32_e32 v18, 0xbfb8aa3b, v16
	v_mul_f32_e32 v19, 0xbfb8aa3b, v17
	v_exp_f32_e32 v18, v18
	v_exp_f32_e32 v19, v19
	v_pk_mul_f32 v[22:23], v[24:25], v[0:1] op_sel_hi:[1,0]
	v_add_f32_e32 v18, 1.0, v18
	v_add_f32_e32 v19, 1.0, v19
	v_rcp_f32_e32 v18, v18
	v_rcp_f32_e32 v19, v19
	v_pk_mul_f32 v[2:3], v[2:3], v[22:23]
	v_pk_mul_f32 v[16:17], v[18:19], v[16:17]
	v_pk_mul_f32 v[4:5], v[4:5], v[14:15]
	v_pk_mul_f32 v[2:3], v[16:17], v[2:3]
	v_lshlrev_b32_e32 v16, 16, v21
	v_and_b32_e32 v17, 0xffff0000, v21
	v_mul_f32_e32 v18, 0xbfb8aa3b, v16
	v_mul_f32_e32 v14, 0xbfb8aa3b, v17
	v_exp_f32_e32 v18, v18
	v_exp_f32_e32 v14, v14
	v_cvt_pk_bf16_f32 v2, v2, v3
	v_add_f32_e32 v18, 1.0, v18
	v_add_f32_e32 v14, 1.0, v14
	v_rcp_f32_e32 v18, v18
	v_rcp_f32_e32 v19, v14
	s_nop 0
	v_pk_mul_f32 v[14:15], v[18:19], v[16:17]
	s_nop 0
	v_pk_mul_f32 v[4:5], v[14:15], v[4:5]
	s_nop 0
	v_cvt_pk_bf16_f32 v3, v4, v5
	global_store_dwordx2 v[10:11], v[2:3], off offset:96
	s_nop 1
	v_mov_b64_e32 v[2:3], v[170:171]
	s_nop 0
	s_nop 1
	v_mov_b64_e32 v[12:13], v[164:165]
	v_mov_b64_e32 v[14:15], v[166:167]
	v_readlane_b32 s3, v252, 9
	s_waitcnt lgkmcnt(0)
	v_lshlrev_b32_e32 v4, 16, v2
	v_and_b32_e32 v5, 0xffff0000, v2
	v_mul_f32_e32 v2, 0xbfb8aa3b, v4
	v_exp_f32_e32 v2, v2
	v_pk_mul_f32 v[8:9], v[12:13], v[8:9]
	v_pk_mul_f32 v[6:7], v[14:15], v[6:7]
	v_add_f32_e32 v2, 1.0, v2
	v_rcp_f32_e32 v16, v2
	v_mul_f32_e32 v2, 0xbfb8aa3b, v5
	v_exp_f32_e32 v2, v2
	s_nop 0
	v_add_f32_e32 v2, 1.0, v2
	v_rcp_f32_e32 v17, v2
	v_lshlrev_b32_e32 v2, 16, v3
	v_and_b32_e32 v3, 0xffff0000, v3
	v_mul_f32_e32 v0, 0xbfb8aa3b, v3
	v_pk_mul_f32 v[4:5], v[16:17], v[4:5]
	v_exp_f32_e32 v0, v0
	v_pk_mul_f32 v[4:5], v[4:5], v[8:9]
	v_mul_f32_e32 v8, 0xbfb8aa3b, v2
	v_exp_f32_e32 v8, v8
	v_add_f32_e32 v0, 1.0, v0
	v_rcp_f32_e32 v9, v0
	v_cvt_pk_bf16_f32 v4, v4, v5
	v_add_f32_e32 v8, 1.0, v8
	v_rcp_f32_e32 v8, v8
	s_nop 0
	v_pk_mul_f32 v[2:3], v[8:9], v[2:3]
	s_nop 0
	v_pk_mul_f32 v[2:3], v[2:3], v[6:7]
	s_nop 0
	v_cvt_pk_bf16_f32 v5, v2, v3
	global_store_dwordx2 v[10:11], v[4:5], off offset:112
